# cmp2_tile (compression MLP layer 2): HID rows fetched by coalesced loads, staged in wave-private padded LDS, then read as MFMA fragments
# speedup vs baseline: 1.0178x; 1.0085x over previous
; #define LAS __attribute__((address_space(3)))
; __device__ __forceinline__ int fresh_lane() { int l; asm volatile("v_mbcnt_lo_u32_b32 %0, -1, 0\n\tv_mbcnt_hi_u32_b32 %0, -1, %0" : "=v"(l)); return l; }
; #define MFMA32(a, b, c) __builtin_amdgcn_mfma_f32_32x32x16_bf16(a, b, c, 0, 0, 0)
; __device__ __forceinline__ void cmp2_tile(const Params& P, const Ctx& C, int kv, int pm) {
;     ...
;     const int lane = fresh_lane(), r32 = lane & 31, hi = lane >> 5, tid = C.wave * 64 + lane;
;     const int row0 = pm * 256 + 32 * C.wave;
;     LAS unsigned char* wl = C.lds;
;     { const unsigned char* wsrc = ws + (kv ? WS_W2TV : WS_W2TK);
;       u32x4 x[4];
; #pragma unroll
;       for (int q = 0; q < 4; ++q) x[q] = *(const u32x4*)(wsrc + (size_t)(tid + 512 * q) * 16);
;       __syncthreads();
; #pragma unroll
;       for (int q = 0; q < 4; ++q) { const int idx = tid + 512 * q, r = idx >> 5, sl = idx & 31; *(LAS u32x4*)(wl + r * 512 + ((sl ^ (r & 15)) * 16)) = x[q]; }
;       __syncthreads(); }
;     const bf16_t* HID = (const bf16_t*)(ws + (kv ? WS_HIDV : WS_HIDK)) + (size_t)(row0 + r32) * 256 + 8 * hi;
;     const LAS unsigned char* wr0 = wl + r32 * 512, * wr1 = wl + (32 + r32) * 512;
;     f32x16 a0 = F16Z_, a1 = a0;
; #pragma unroll 8
;     for (int ks = 0; ks < 16; ++ks) { const bf16x8 hf = *(const bf16x8*)(HID + 16 * ks); const int so = (((2 * ks + hi) ^ (r32 & 15)) * 16);
;         a0 = MFMA32(*(const LAS bf16x8*)(wr0 + so), hf, a0); a1 = MFMA32(*(const LAS bf16x8*)(wr1 + so), hf, a1); }
.LBB0_1086:
	s_cmp_eq_u32 s2, 0
	s_cselect_b64 s[14:15], -1, 0
	s_and_b64 s[22:23], s[14:15], exec
	s_waitcnt lgkmcnt(0)
	s_mov_b64 s[12:13], s[4:5]
	s_cselect_b32 s21, s17, 0x1d08000
	v_mbcnt_lo_u32_b32 v17, -1, 0
	v_mbcnt_hi_u32_b32 v17, -1, v17
	s_cselect_b32 s2, s18, 0x34b00000
	v_add_u32_e32 v30, s0, v17
	s_add_u32 s22, s12, s21
	s_addc_u32 s23, s13, 0
	v_ashrrev_i32_e32 v31, 31, v30
	v_add_u32_e32 v34, 0x200, v30
	v_add_u32_e32 v44, 0x400, v30
	v_lshl_add_u64 v[0:1], v[30:31], 4, s[22:23]
	v_ashrrev_i32_e32 v35, 31, v34
	v_ashrrev_i32_e32 v45, 31, v44
	v_add_u32_e32 v46, 0x600, v30
	v_lshl_add_u64 v[2:3], v[34:35], 4, s[22:23]
	global_load_dwordx4 v[18:21], v[0:1], off
	global_load_dwordx4 v[22:25], v[2:3], off
	v_lshl_add_u64 v[0:1], v[44:45], 4, s[22:23]
	v_ashrrev_i32_e32 v47, 31, v46
	v_lshl_add_u64 v[2:3], v[46:47], 4, s[22:23]
	global_load_dwordx4 v[26:29], v[0:1], off
	global_load_dwordx4 v[40:43], v[2:3], off
	v_and_b32_e32 v37, 31, v17
	v_ashrrev_i32_e32 v36, 5, v17
	v_and_b32_e32 v38, 15, v17
	v_ashrrev_i32_e32 v17, 5, v30
	v_lshlrev_b32_e32 v32, 9, v17
	v_bitop3_b32 v17, v17, v37, 15 bitop3:0x6c
	v_ashrrev_i32_e32 v34, 5, v34
	v_ashrrev_i32_e32 v35, 5, v44
	v_ashrrev_i32_e32 v44, 5, v46
	v_lshlrev_b32_e32 v17, 4, v17
	v_lshlrev_b32_e32 v45, 9, v34
	v_bitop3_b32 v34, v34, v37, 15 bitop3:0x6c
	s_lshl_b32 s22, s28, 8
	v_lshlrev_b32_e32 v46, 9, v35
	v_bitop3_b32 v35, v35, v37, 15 bitop3:0x6c
	v_lshlrev_b32_e32 v47, 9, v44
	v_bitop3_b32 v44, v44, v37, 15 bitop3:0x6c
	v_add3_u32 v17, 0, v32, v17
	v_lshlrev_b32_e32 v32, 4, v34
	s_add_i32 s22, s22, s16
	v_lshlrev_b32_e32 v34, 4, v35
	v_lshlrev_b32_e32 v35, 4, v44
	v_add3_u32 v44, 0, v45, v32
	v_add_u32_e32 v32, s22, v37
	v_lshlrev_b32_e32 v30, 3, v36
	v_add3_u32 v45, 0, v46, v34
	v_add3_u32 v46, 0, v47, v35
	v_lshlrev_b64 v[34:35], 9, v[32:33]
	v_ashrrev_i32_e32 v31, 31, v30
	v_lshl_add_u64 v[34:35], s[2:3], 0, v[34:35]
	v_lshl_add_u64 v[30:31], v[30:31], 1, v[34:35]
	v_lshl_add_u64 v[30:31], s[12:13], 0, v[30:31]
	s_mov_b32 s21, 0
	v_mov_b32_e32 v0, 0
	v_mov_b32_e32 v1, v33
	v_mov_b32_e32 v2, v33
	v_mov_b32_e32 v3, v33
	v_mov_b32_e32 v4, v33
	v_mov_b32_e32 v5, v33
	v_mov_b32_e32 v6, v33
	v_mov_b32_e32 v7, v33
	v_mov_b32_e32 v8, v33
	v_mov_b32_e32 v9, v33
	v_mov_b32_e32 v10, v33
	v_mov_b32_e32 v11, v33
	v_mov_b32_e32 v12, v33
	v_mov_b32_e32 v13, v33
	v_mov_b32_e32 v14, v33
	v_mov_b32_e32 v15, v33
	v_mov_b32_e32 v16, 0
	v_lshl_add_u32 v39, v37, 9, 0
	s_barrier
	v_lshl_add_u64 v[34:35], v[30:31], 0, s[6:7]
	v_mov_b32_e32 v30, v33
	v_mov_b32_e32 v31, v33
	s_waitcnt vmcnt(3)
	ds_write_b128 v17, v[18:21]
	s_waitcnt vmcnt(2)
	ds_write_b128 v44, v[22:25]
	s_waitcnt vmcnt(1)
	ds_write_b128 v45, v[26:29]
	s_waitcnt vmcnt(0)
	ds_write_b128 v46, v[40:43]
	v_mov_b32_e32 v17, v33
	v_mov_b32_e32 v18, v33
	v_mov_b32_e32 v19, v33
	v_mov_b32_e32 v20, v33
	v_mov_b32_e32 v21, v33
	v_mov_b32_e32 v22, v33
	v_mov_b32_e32 v23, v33
	v_mov_b32_e32 v24, v33
	v_mov_b32_e32 v25, v33
	v_mov_b32_e32 v26, v33
	v_mov_b32_e32 v27, v33
	v_mov_b32_e32 v28, v33
	v_mov_b32_e32 v29, v33
	s_waitcnt lgkmcnt(0)
	s_barrier
	v_readfirstlane_b32 s98, v34
	v_readfirstlane_b32 s99, v35
	v_readlane_b32 s100, v254, 6
	v_mbcnt_lo_u32_b32 v156, -1, 0
	v_mbcnt_hi_u32_b32 v156, -1, v156
	v_lshrrev_b32_e32 v154, 4, v156
	v_and_b32_e32 v157, 15, v156
	v_lshlrev_b32_e32 v152, 9, v154
	v_lshl_add_u32 v152, v157, 4, v152
	v_add_u32_e32 v152, 0x1000, v152
	v_add_u32_e32 v153, 0x2000, v152
	v_mul_u32_u24_e32 v154, 272, v154
	v_lshl_add_u32 v154, v157, 4, v154
	s_mul_i32 s100, s100, 8704
	s_add_u32 s100, s100, 0x8000
	v_add_u32_e32 v154, s100, v154
	v_mul_u32_u24_e32 v155, 272, v37
	v_lshl_add_u32 v155, v36, 4, v155
	v_add_u32_e32 v155, s100, v155
	s_sub_u32 s98, s98, 0xe0
	s_subb_u32 s99, s99, 0
	global_load_dwordx4 v[64:67], v152, s[98:99] offset:-4096
	global_load_dwordx4 v[68:71], v152, s[98:99] offset:-2048
	global_load_dwordx4 v[72:75], v152, s[98:99] offset:0
	global_load_dwordx4 v[76:79], v152, s[98:99] offset:2048
	global_load_dwordx4 v[80:83], v153, s[98:99] offset:-4096
	global_load_dwordx4 v[84:87], v153, s[98:99] offset:-2048
	global_load_dwordx4 v[88:91], v153, s[98:99] offset:0
	global_load_dwordx4 v[92:95], v153, s[98:99] offset:2048
	global_load_dwordx4 v[96:99], v152, s[98:99] offset:-3840
	global_load_dwordx4 v[100:103], v152, s[98:99] offset:-1792
	global_load_dwordx4 v[104:107], v152, s[98:99] offset:256
	global_load_dwordx4 v[108:111], v152, s[98:99] offset:2304
	global_load_dwordx4 v[112:115], v153, s[98:99] offset:-3840
	global_load_dwordx4 v[116:119], v153, s[98:99] offset:-1792
	global_load_dwordx4 v[120:123], v153, s[98:99] offset:256
	global_load_dwordx4 v[124:127], v153, s[98:99] offset:2304
	s_waitcnt vmcnt(8)
	ds_write_b128 v154, v[64:67] offset:0
	ds_write_b128 v154, v[68:71] offset:1088
	ds_write_b128 v154, v[72:75] offset:2176
	ds_write_b128 v154, v[76:79] offset:3264
	ds_write_b128 v154, v[80:83] offset:4352
	ds_write_b128 v154, v[84:87] offset:5440
	ds_write_b128 v154, v[88:91] offset:6528
	ds_write_b128 v154, v[92:95] offset:7616
	v_add_u32_e32 v156, 0, v36
	v_xor_b32_e32 v156, v156, v38
	v_lshl_add_u32 v157, v156, 4, v39
	ds_read_b128 v[128:131], v155 offset:0
	ds_read_b128 v[136:139], v157
	ds_read_b128 v[144:147], v157 offset:16384
	v_add_u32_e32 v156, 2, v36
	v_xor_b32_e32 v156, v156, v38
	v_lshl_add_u32 v157, v156, 4, v39
	ds_read_b128 v[132:135], v155 offset:32
	ds_read_b128 v[140:143], v157
	ds_read_b128 v[148:151], v157 offset:16384
	s_waitcnt lgkmcnt(4)
	v_mfma_f32_32x32x16_bf16 v[16:31], v[136:139], v[128:131], v[16:31]
	s_waitcnt lgkmcnt(3)
; #define LAS __attribute__((address_space(3)))
; #define MFMA32(a, b, c) __builtin_amdgcn_mfma_f32_32x32x16_bf16(a, b, c, 0, 0, 0)
; __device__ __forceinline__ void cmp2_tile(const Params& P, const Ctx& C, int kv, int pm) {
;     ...
; #pragma unroll 8
;     for (int ks = 0; ks < 16; ++ks) { const bf16x8 hf = *(const bf16x8*)(HID + 16 * ks); const int so = (((2 * ks + hi) ^ (r32 & 15)) * 16);
;         a0 = MFMA32(*(const LAS bf16x8*)(wr0 + so), hf, a0); a1 = MFMA32(*(const LAS bf16x8*)(wr1 + so), hf, a1); }
	v_mfma_f32_32x32x16_bf16 v[0:15], v[144:147], v[128:131], v[0:15]
	v_add_u32_e32 v156, 4, v36
	v_xor_b32_e32 v156, v156, v38
	v_lshl_add_u32 v157, v156, 4, v39
	ds_read_b128 v[128:131], v155 offset:64
	ds_read_b128 v[136:139], v157
	ds_read_b128 v[144:147], v157 offset:16384
	s_waitcnt lgkmcnt(4)
	v_mfma_f32_32x32x16_bf16 v[16:31], v[140:143], v[132:135], v[16:31]
	s_waitcnt lgkmcnt(3)
	v_mfma_f32_32x32x16_bf16 v[0:15], v[148:151], v[132:135], v[0:15]
	v_add_u32_e32 v156, 6, v36
	v_xor_b32_e32 v156, v156, v38
	v_lshl_add_u32 v157, v156, 4, v39
	ds_read_b128 v[132:135], v155 offset:96
	ds_read_b128 v[140:143], v157
	ds_read_b128 v[148:151], v157 offset:16384
	s_waitcnt lgkmcnt(4)
	v_mfma_f32_32x32x16_bf16 v[16:31], v[136:139], v[128:131], v[16:31]
	s_waitcnt lgkmcnt(3)
	v_mfma_f32_32x32x16_bf16 v[0:15], v[144:147], v[128:131], v[0:15]
	v_add_u32_e32 v156, 8, v36
	v_xor_b32_e32 v156, v156, v38
	v_lshl_add_u32 v157, v156, 4, v39
	ds_read_b128 v[128:131], v155 offset:128
	ds_read_b128 v[136:139], v157
	ds_read_b128 v[144:147], v157 offset:16384
	s_waitcnt lgkmcnt(4)
	v_mfma_f32_32x32x16_bf16 v[16:31], v[140:143], v[132:135], v[16:31]
	s_waitcnt lgkmcnt(3)
	v_mfma_f32_32x32x16_bf16 v[0:15], v[148:151], v[132:135], v[0:15]
	v_add_u32_e32 v156, 10, v36
	v_xor_b32_e32 v156, v156, v38
	v_lshl_add_u32 v157, v156, 4, v39
	ds_read_b128 v[132:135], v155 offset:160
	ds_read_b128 v[140:143], v157
	ds_read_b128 v[148:151], v157 offset:16384
	s_waitcnt lgkmcnt(4)
	v_mfma_f32_32x32x16_bf16 v[16:31], v[136:139], v[128:131], v[16:31]
	s_waitcnt lgkmcnt(3)
	v_mfma_f32_32x32x16_bf16 v[0:15], v[144:147], v[128:131], v[0:15]
	v_add_u32_e32 v156, 12, v36
	v_xor_b32_e32 v156, v156, v38
	v_lshl_add_u32 v157, v156, 4, v39
	ds_read_b128 v[128:131], v155 offset:192
	ds_read_b128 v[136:139], v157
	ds_read_b128 v[144:147], v157 offset:16384
	s_waitcnt lgkmcnt(4)
	v_mfma_f32_32x32x16_bf16 v[16:31], v[140:143], v[132:135], v[16:31]
	s_waitcnt lgkmcnt(3)
	v_mfma_f32_32x32x16_bf16 v[0:15], v[148:151], v[132:135], v[0:15]
	v_add_u32_e32 v156, 14, v36
	v_xor_b32_e32 v156, v156, v38
	v_lshl_add_u32 v157, v156, 4, v39
	ds_read_b128 v[132:135], v155 offset:224
	ds_read_b128 v[140:143], v157
	ds_read_b128 v[148:151], v157 offset:16384
	s_waitcnt lgkmcnt(4)
	v_mfma_f32_32x32x16_bf16 v[16:31], v[136:139], v[128:131], v[16:31]
	s_waitcnt lgkmcnt(3)
	v_mfma_f32_32x32x16_bf16 v[0:15], v[144:147], v[128:131], v[0:15]
	s_waitcnt lgkmcnt(1)
	v_mfma_f32_32x32x16_bf16 v[16:31], v[140:143], v[132:135], v[16:31]
	s_waitcnt lgkmcnt(0)
	v_mfma_f32_32x32x16_bf16 v[0:15], v[148:151], v[132:135], v[0:15]
	s_waitcnt vmcnt(0)
	ds_write_b128 v154, v[96:99] offset:0
	ds_write_b128 v154, v[100:103] offset:1088
	ds_write_b128 v154, v[104:107] offset:2176
	ds_write_b128 v154, v[108:111] offset:3264
	ds_write_b128 v154, v[112:115] offset:4352
	ds_write_b128 v154, v[116:119] offset:5440
	ds_write_b128 v154, v[120:123] offset:6528
	ds_write_b128 v154, v[124:127] offset:7616
	v_add_u32_e32 v156, 16, v36
	v_xor_b32_e32 v156, v156, v38
	v_lshl_add_u32 v157, v156, 4, v39
	ds_read_b128 v[128:131], v155 offset:0
	ds_read_b128 v[136:139], v157
	ds_read_b128 v[144:147], v157 offset:16384
	v_add_u32_e32 v156, 18, v36
	v_xor_b32_e32 v156, v156, v38
	v_lshl_add_u32 v157, v156, 4, v39
	ds_read_b128 v[132:135], v155 offset:32
	ds_read_b128 v[140:143], v157
	ds_read_b128 v[148:151], v157 offset:16384
	s_waitcnt lgkmcnt(4)
	v_mfma_f32_32x32x16_bf16 v[16:31], v[136:139], v[128:131], v[16:31]
	s_waitcnt lgkmcnt(3)
	v_mfma_f32_32x32x16_bf16 v[0:15], v[144:147], v[128:131], v[0:15]
	v_add_u32_e32 v156, 20, v36
	v_xor_b32_e32 v156, v156, v38
	v_lshl_add_u32 v157, v156, 4, v39
	ds_read_b128 v[128:131], v155 offset:64
	ds_read_b128 v[136:139], v157
	ds_read_b128 v[144:147], v157 offset:16384
	s_waitcnt lgkmcnt(4)
; #define LAS __attribute__((address_space(3)))
; __device__ __forceinline__ unsigned pk2(float lo, float hi) { return cvt_pk_bf16(lo, hi); }
; #define MFMA32(a, b, c) __builtin_amdgcn_mfma_f32_32x32x16_bf16(a, b, c, 0, 0, 0)
; __device__ __forceinline__ void cmp2_tile(const Params& P, const Ctx& C, int kv, int pm) {
;     ...
; #pragma unroll 8
;     for (int ks = 0; ks < 16; ++ks) { const bf16x8 hf = *(const bf16x8*)(HID + 16 * ks); const int so = (((2 * ks + hi) ^ (r32 & 15)) * 16);
;         a0 = MFMA32(*(const LAS bf16x8*)(wr0 + so), hf, a0); a1 = MFMA32(*(const LAS bf16x8*)(wr1 + so), hf, a1); }
;     bf16_t* O = (bf16_t*)(ws + (kv ? WS_VCC : WS_KCC)) + (size_t)(row0 + r32) * 64;
; #pragma unroll
;     for (int rq = 0; rq < 4; ++rq) { u32x2 w;
;         w.x = pk2(a0[4 * rq], a0[4 * rq + 1]); w.y = pk2(a0[4 * rq + 2], a0[4 * rq + 3]); *(u32x2*)(O + 8 * rq + 4 * hi) = w;
;         w.x = pk2(a1[4 * rq], a1[4 * rq + 1]); w.y = pk2(a1[4 * rq + 2], a1[4 * rq + 3]); *(u32x2*)(O + 32 + 8 * rq + 4 * hi) = w; }
	v_mfma_f32_32x32x16_bf16 v[16:31], v[140:143], v[132:135], v[16:31]
	s_waitcnt lgkmcnt(3)
	v_mfma_f32_32x32x16_bf16 v[0:15], v[148:151], v[132:135], v[0:15]
	v_add_u32_e32 v156, 22, v36
	v_xor_b32_e32 v156, v156, v38
	v_lshl_add_u32 v157, v156, 4, v39
	ds_read_b128 v[132:135], v155 offset:96
	ds_read_b128 v[140:143], v157
	ds_read_b128 v[148:151], v157 offset:16384
	s_waitcnt lgkmcnt(4)
	v_mfma_f32_32x32x16_bf16 v[16:31], v[136:139], v[128:131], v[16:31]
	s_waitcnt lgkmcnt(3)
	v_mfma_f32_32x32x16_bf16 v[0:15], v[144:147], v[128:131], v[0:15]
	v_add_u32_e32 v156, 24, v36
	v_xor_b32_e32 v156, v156, v38
	v_lshl_add_u32 v157, v156, 4, v39
	ds_read_b128 v[128:131], v155 offset:128
	ds_read_b128 v[136:139], v157
	ds_read_b128 v[144:147], v157 offset:16384
	s_waitcnt lgkmcnt(4)
	v_mfma_f32_32x32x16_bf16 v[16:31], v[140:143], v[132:135], v[16:31]
	s_waitcnt lgkmcnt(3)
	v_mfma_f32_32x32x16_bf16 v[0:15], v[148:151], v[132:135], v[0:15]
	v_add_u32_e32 v156, 26, v36
	v_xor_b32_e32 v156, v156, v38
	v_lshl_add_u32 v157, v156, 4, v39
	ds_read_b128 v[132:135], v155 offset:160
	ds_read_b128 v[140:143], v157
	ds_read_b128 v[148:151], v157 offset:16384
	s_waitcnt lgkmcnt(4)
	v_mfma_f32_32x32x16_bf16 v[16:31], v[136:139], v[128:131], v[16:31]
	s_waitcnt lgkmcnt(3)
	v_mfma_f32_32x32x16_bf16 v[0:15], v[144:147], v[128:131], v[0:15]
	v_add_u32_e32 v156, 28, v36
	v_xor_b32_e32 v156, v156, v38
	v_lshl_add_u32 v157, v156, 4, v39
	ds_read_b128 v[128:131], v155 offset:192
	ds_read_b128 v[136:139], v157
	ds_read_b128 v[144:147], v157 offset:16384
	s_waitcnt lgkmcnt(4)
	v_mfma_f32_32x32x16_bf16 v[16:31], v[140:143], v[132:135], v[16:31]
	s_waitcnt lgkmcnt(3)
	v_mfma_f32_32x32x16_bf16 v[0:15], v[148:151], v[132:135], v[0:15]
	v_add_u32_e32 v156, 30, v36
	v_xor_b32_e32 v156, v156, v38
	v_lshl_add_u32 v157, v156, 4, v39
	ds_read_b128 v[132:135], v155 offset:224
	ds_read_b128 v[140:143], v157
	ds_read_b128 v[148:151], v157 offset:16384
	s_waitcnt lgkmcnt(4)
	v_mfma_f32_32x32x16_bf16 v[16:31], v[136:139], v[128:131], v[16:31]
	s_waitcnt lgkmcnt(3)
	v_mfma_f32_32x32x16_bf16 v[0:15], v[144:147], v[128:131], v[0:15]
	s_waitcnt lgkmcnt(1)
	v_mfma_f32_32x32x16_bf16 v[16:31], v[140:143], v[132:135], v[16:31]
	s_waitcnt lgkmcnt(0)
	v_mfma_f32_32x32x16_bf16 v[0:15], v[148:151], v[132:135], v[0:15]
	s_nop 0
	s_and_b64 s[14:15], s[14:15], exec
	s_cselect_b32 s2, s19, 0x37700000
	v_or_b32_e32 v32, s22, v37
	s_add_u32 s12, s12, s2
	s_addc_u32 s13, s13, 0
	v_lshlrev_b64 v[34:35], 7, v[32:33]
	v_lshlrev_b32_e32 v36, 2, v36
	v_lshl_add_u64 v[34:35], s[12:13], 0, v[34:35]
	v_ashrrev_i32_e32 v37, 31, v36
	v_lshl_add_u64 v[34:35], v[36:37], 1, v[34:35]
	v_cvt_pk_bf16_f32 v16, v16, v17
	v_cvt_pk_bf16_f32 v17, v18, v19
	global_store_dwordx2 v[34:35], v[16:17], off
	v_cvt_pk_bf16_f32 v0, v0, v1
	v_cvt_pk_bf16_f32 v1, v2, v3
	s_add_i32 s20, s20, 1
	global_store_dwordx2 v[34:35], v[0:1], off offset:64
	v_cvt_pk_bf16_f32 v0, v20, v21
	v_cvt_pk_bf16_f32 v1, v22, v23
	s_mul_i32 s2, s20, s68
	global_store_dwordx2 v[34:35], v[0:1], off offset:16
	v_cvt_pk_bf16_f32 v0, v4, v5
	v_cvt_pk_bf16_f32 v1, v6, v7
	s_add_i32 s12, s2, s87
	global_store_dwordx2 v[34:35], v[0:1], off offset:80
	v_cvt_pk_bf16_f32 v0, v24, v25
	v_cvt_pk_bf16_f32 v1, v26, v27
	s_and_b32 s2, s12, 0xff
	global_store_dwordx2 v[34:35], v[0:1], off offset:32
	v_cvt_pk_bf16_f32 v0, v8, v9
	v_cvt_pk_bf16_f32 v1, v10, v11
	s_add_i32 s28, s2, 16
	s_ashr_i32 s2, s12, 8
	global_store_dwordx2 v[34:35], v[0:1], off offset:96
	v_cvt_pk_bf16_f32 v0, v28, v29
	v_cvt_pk_bf16_f32 v1, v30, v31
	s_cmpk_gt_i32 s12, 0x1ff
	global_store_dwordx2 v[34:35], v[0:1], off offset:48
	v_cvt_pk_bf16_f32 v0, v12, v13
	v_cvt_pk_bf16_f32 v1, v14, v15
	global_store_dwordx2 v[34:35], v[0:1], off offset:112
	s_cbranch_scc0 .LBB0_1086

; #define LAS __attribute__((address_space(3)))
; __device__ __forceinline__ int fresh_lane() { int l; asm volatile("v_mbcnt_lo_u32_b32 %0, -1, 0\n\tv_mbcnt_hi_u32_b32 %0, -1, %0" : "=v"(l)); return l; }
; #define MFMA32(a, b, c) __builtin_amdgcn_mfma_f32_32x32x16_bf16(a, b, c, 0, 0, 0)
; __device__ __forceinline__ void cmp2_tile(const Params& P, const Ctx& C, int kv, int pm) {
;     ...
;     const int lane = fresh_lane(), r32 = lane & 31, hi = lane >> 5, tid = C.wave * 64 + lane;
;     const int row0 = pm * 256 + 32 * C.wave;
;     LAS unsigned char* wl = C.lds;
;     { const unsigned char* wsrc = ws + (kv ? WS_W2TV : WS_W2TK);
;       u32x4 x[4];
; #pragma unroll
;       for (int q = 0; q < 4; ++q) x[q] = *(const u32x4*)(wsrc + (size_t)(tid + 512 * q) * 16);
;       __syncthreads();
; #pragma unroll
;       for (int q = 0; q < 4; ++q) { const int idx = tid + 512 * q, r = idx >> 5, sl = idx & 31; *(LAS u32x4*)(wl + r * 512 + ((sl ^ (r & 15)) * 16)) = x[q]; }
;       __syncthreads(); }
;     const bf16_t* HID = (const bf16_t*)(ws + (kv ? WS_HIDV : WS_HIDK)) + (size_t)(row0 + r32) * 256 + 8 * hi;
;     const LAS unsigned char* wr0 = wl + r32 * 512, * wr1 = wl + (32 + r32) * 512;
;     f32x16 a0 = F16Z_, a1 = a0;
; #pragma unroll 8
;     for (int ks = 0; ks < 16; ++ks) { const bf16x8 hf = *(const bf16x8*)(HID + 16 * ks); const int so = (((2 * ks + hi) ^ (r32 & 15)) * 16);
;         a0 = MFMA32(*(const LAS bf16x8*)(wr0 + so), hf, a0); a1 = MFMA32(*(const LAS bf16x8*)(wr1 + so), hf, a1); }
.LBB0_1112:
	s_cmp_eq_u32 s6, 0
	s_cselect_b64 s[16:17], -1, 0
	s_and_b64 s[22:23], s[16:17], exec
	s_waitcnt lgkmcnt(0)
	s_mov_b64 s[14:15], s[2:3]
	s_cselect_b32 s22, s18, 0x1d08000
	v_mbcnt_lo_u32_b32 v17, -1, 0
	v_mbcnt_hi_u32_b32 v17, -1, v17
	s_cselect_b32 s6, s19, 0x34b00000
	v_add_u32_e32 v30, s0, v17
	s_add_u32 s22, s14, s22
	s_addc_u32 s23, s15, 0
	v_ashrrev_i32_e32 v31, 31, v30
	v_add_u32_e32 v34, 0x200, v30
	v_add_u32_e32 v44, 0x400, v30
	v_lshl_add_u64 v[0:1], v[30:31], 4, s[22:23]
	v_ashrrev_i32_e32 v35, 31, v34
	v_ashrrev_i32_e32 v45, 31, v44
	v_add_u32_e32 v46, 0x600, v30
	v_lshl_add_u64 v[2:3], v[34:35], 4, s[22:23]
	global_load_dwordx4 v[18:21], v[0:1], off
	global_load_dwordx4 v[22:25], v[2:3], off
	v_lshl_add_u64 v[0:1], v[44:45], 4, s[22:23]
	v_ashrrev_i32_e32 v47, 31, v46
	v_lshl_add_u64 v[2:3], v[46:47], 4, s[22:23]
	global_load_dwordx4 v[26:29], v[0:1], off
	global_load_dwordx4 v[40:43], v[2:3], off
	v_and_b32_e32 v37, 31, v17
	v_ashrrev_i32_e32 v36, 5, v17
	v_and_b32_e32 v38, 15, v17
	v_ashrrev_i32_e32 v17, 5, v30
	v_lshlrev_b32_e32 v32, 9, v17
	v_bitop3_b32 v17, v17, v37, 15 bitop3:0x6c
	v_ashrrev_i32_e32 v34, 5, v34
	v_ashrrev_i32_e32 v35, 5, v44
	v_ashrrev_i32_e32 v44, 5, v46
	v_lshlrev_b32_e32 v17, 4, v17
	v_lshlrev_b32_e32 v45, 9, v34
	v_bitop3_b32 v34, v34, v37, 15 bitop3:0x6c
	s_lshl_b32 s23, s40, 8
	v_lshlrev_b32_e32 v46, 9, v35
	v_bitop3_b32 v35, v35, v37, 15 bitop3:0x6c
	v_lshlrev_b32_e32 v47, 9, v44
	v_bitop3_b32 v44, v44, v37, 15 bitop3:0x6c
	v_add3_u32 v17, 0, v32, v17
	v_lshlrev_b32_e32 v32, 4, v34
	s_add_i32 s23, s23, s1
	v_lshlrev_b32_e32 v34, 4, v35
	v_lshlrev_b32_e32 v35, 4, v44
	v_add3_u32 v44, 0, v45, v32
	v_add_u32_e32 v32, s23, v37
	v_lshlrev_b32_e32 v30, 3, v36
	v_add3_u32 v45, 0, v46, v34
	v_add3_u32 v46, 0, v47, v35
	v_lshlrev_b64 v[34:35], 9, v[32:33]
	v_ashrrev_i32_e32 v31, 31, v30
	v_lshl_add_u64 v[34:35], s[6:7], 0, v[34:35]
	v_lshl_add_u64 v[30:31], v[30:31], 1, v[34:35]
	v_lshl_add_u64 v[30:31], s[14:15], 0, v[30:31]
	s_mov_b32 s22, 0
	v_mov_b32_e32 v0, 0
	v_mov_b32_e32 v1, v33
	v_mov_b32_e32 v2, v33
	v_mov_b32_e32 v3, v33
	v_mov_b32_e32 v4, v33
	v_mov_b32_e32 v5, v33
	v_mov_b32_e32 v6, v33
	v_mov_b32_e32 v7, v33
	v_mov_b32_e32 v8, v33
	v_mov_b32_e32 v9, v33
	v_mov_b32_e32 v10, v33
	v_mov_b32_e32 v11, v33
	v_mov_b32_e32 v12, v33
	v_mov_b32_e32 v13, v33
	v_mov_b32_e32 v14, v33
	v_mov_b32_e32 v15, v33
	v_mov_b32_e32 v16, 0
	v_lshl_add_u32 v39, v37, 9, 0
	s_barrier
	v_lshl_add_u64 v[34:35], v[30:31], 0, s[10:11]
	v_mov_b32_e32 v30, v33
	v_mov_b32_e32 v31, v33
	s_waitcnt vmcnt(3)
	ds_write_b128 v17, v[18:21]
	s_waitcnt vmcnt(2)
	ds_write_b128 v44, v[22:25]
	s_waitcnt vmcnt(1)
	ds_write_b128 v45, v[26:29]
	s_waitcnt vmcnt(0)
	ds_write_b128 v46, v[40:43]
	v_mov_b32_e32 v17, v33
	v_mov_b32_e32 v18, v33
	v_mov_b32_e32 v19, v33
	v_mov_b32_e32 v20, v33
	v_mov_b32_e32 v21, v33
	v_mov_b32_e32 v22, v33
	v_mov_b32_e32 v23, v33
	v_mov_b32_e32 v24, v33
	v_mov_b32_e32 v25, v33
	v_mov_b32_e32 v26, v33
	v_mov_b32_e32 v27, v33
	v_mov_b32_e32 v28, v33
	v_mov_b32_e32 v29, v33
	s_waitcnt lgkmcnt(0)
	s_barrier
	v_readfirstlane_b32 s98, v34
	v_readfirstlane_b32 s99, v35
	v_readlane_b32 s100, v254, 6
	v_mbcnt_lo_u32_b32 v156, -1, 0
	v_mbcnt_hi_u32_b32 v156, -1, v156
	v_lshrrev_b32_e32 v154, 4, v156
	v_and_b32_e32 v157, 15, v156
	v_lshlrev_b32_e32 v152, 9, v154
	v_lshl_add_u32 v152, v157, 4, v152
	v_add_u32_e32 v152, 0x1000, v152
	v_add_u32_e32 v153, 0x2000, v152
	v_mul_u32_u24_e32 v154, 272, v154
	v_lshl_add_u32 v154, v157, 4, v154
	s_mul_i32 s100, s100, 8704
	s_add_u32 s100, s100, 0x8000
	v_add_u32_e32 v154, s100, v154
	v_mul_u32_u24_e32 v155, 272, v37
	v_lshl_add_u32 v155, v36, 4, v155
	v_add_u32_e32 v155, s100, v155
	s_sub_u32 s98, s98, 0xe0
	s_subb_u32 s99, s99, 0
	global_load_dwordx4 v[64:67], v152, s[98:99] offset:-4096
	global_load_dwordx4 v[68:71], v152, s[98:99] offset:-2048
	global_load_dwordx4 v[72:75], v152, s[98:99] offset:0
	global_load_dwordx4 v[76:79], v152, s[98:99] offset:2048
	global_load_dwordx4 v[80:83], v153, s[98:99] offset:-4096
	global_load_dwordx4 v[84:87], v153, s[98:99] offset:-2048
	global_load_dwordx4 v[88:91], v153, s[98:99] offset:0
	global_load_dwordx4 v[92:95], v153, s[98:99] offset:2048
	global_load_dwordx4 v[96:99], v152, s[98:99] offset:-3840
	global_load_dwordx4 v[100:103], v152, s[98:99] offset:-1792
	global_load_dwordx4 v[104:107], v152, s[98:99] offset:256
	global_load_dwordx4 v[108:111], v152, s[98:99] offset:2304
	global_load_dwordx4 v[112:115], v153, s[98:99] offset:-3840
	global_load_dwordx4 v[116:119], v153, s[98:99] offset:-1792
	global_load_dwordx4 v[120:123], v153, s[98:99] offset:256
	global_load_dwordx4 v[124:127], v153, s[98:99] offset:2304
	s_waitcnt vmcnt(8)
	ds_write_b128 v154, v[64:67] offset:0
	ds_write_b128 v154, v[68:71] offset:1088
	ds_write_b128 v154, v[72:75] offset:2176
	ds_write_b128 v154, v[76:79] offset:3264
	ds_write_b128 v154, v[80:83] offset:4352
	ds_write_b128 v154, v[84:87] offset:5440
	ds_write_b128 v154, v[88:91] offset:6528
	ds_write_b128 v154, v[92:95] offset:7616
	v_add_u32_e32 v156, 0, v36
	v_xor_b32_e32 v156, v156, v38
	v_lshl_add_u32 v157, v156, 4, v39
	ds_read_b128 v[128:131], v155 offset:0
	ds_read_b128 v[136:139], v157
	ds_read_b128 v[144:147], v157 offset:16384
	v_add_u32_e32 v156, 2, v36
	v_xor_b32_e32 v156, v156, v38
	v_lshl_add_u32 v157, v156, 4, v39
	ds_read_b128 v[132:135], v155 offset:32
	ds_read_b128 v[140:143], v157
	ds_read_b128 v[148:151], v157 offset:16384
	s_waitcnt lgkmcnt(4)
	v_mfma_f32_32x32x16_bf16 v[16:31], v[136:139], v[128:131], v[16:31]
	s_waitcnt lgkmcnt(3)
; #define LAS __attribute__((address_space(3)))
; #define MFMA32(a, b, c) __builtin_amdgcn_mfma_f32_32x32x16_bf16(a, b, c, 0, 0, 0)
; __device__ __forceinline__ void cmp2_tile(const Params& P, const Ctx& C, int kv, int pm) {
;     ...
; #pragma unroll 8
;     for (int ks = 0; ks < 16; ++ks) { const bf16x8 hf = *(const bf16x8*)(HID + 16 * ks); const int so = (((2 * ks + hi) ^ (r32 & 15)) * 16);
;         a0 = MFMA32(*(const LAS bf16x8*)(wr0 + so), hf, a0); a1 = MFMA32(*(const LAS bf16x8*)(wr1 + so), hf, a1); }
	v_mfma_f32_32x32x16_bf16 v[0:15], v[144:147], v[128:131], v[0:15]
	v_add_u32_e32 v156, 4, v36
	v_xor_b32_e32 v156, v156, v38
	v_lshl_add_u32 v157, v156, 4, v39
	ds_read_b128 v[128:131], v155 offset:64
	ds_read_b128 v[136:139], v157
	ds_read_b128 v[144:147], v157 offset:16384
	s_waitcnt lgkmcnt(4)
	v_mfma_f32_32x32x16_bf16 v[16:31], v[140:143], v[132:135], v[16:31]
	s_waitcnt lgkmcnt(3)
	v_mfma_f32_32x32x16_bf16 v[0:15], v[148:151], v[132:135], v[0:15]
	v_add_u32_e32 v156, 6, v36
	v_xor_b32_e32 v156, v156, v38
	v_lshl_add_u32 v157, v156, 4, v39
	ds_read_b128 v[132:135], v155 offset:96
	ds_read_b128 v[140:143], v157
	ds_read_b128 v[148:151], v157 offset:16384
	s_waitcnt lgkmcnt(4)
	v_mfma_f32_32x32x16_bf16 v[16:31], v[136:139], v[128:131], v[16:31]
	s_waitcnt lgkmcnt(3)
	v_mfma_f32_32x32x16_bf16 v[0:15], v[144:147], v[128:131], v[0:15]
	v_add_u32_e32 v156, 8, v36
	v_xor_b32_e32 v156, v156, v38
	v_lshl_add_u32 v157, v156, 4, v39
	ds_read_b128 v[128:131], v155 offset:128
	ds_read_b128 v[136:139], v157
	ds_read_b128 v[144:147], v157 offset:16384
	s_waitcnt lgkmcnt(4)
	v_mfma_f32_32x32x16_bf16 v[16:31], v[140:143], v[132:135], v[16:31]
	s_waitcnt lgkmcnt(3)
	v_mfma_f32_32x32x16_bf16 v[0:15], v[148:151], v[132:135], v[0:15]
	v_add_u32_e32 v156, 10, v36
	v_xor_b32_e32 v156, v156, v38
	v_lshl_add_u32 v157, v156, 4, v39
	ds_read_b128 v[132:135], v155 offset:160
	ds_read_b128 v[140:143], v157
	ds_read_b128 v[148:151], v157 offset:16384
	s_waitcnt lgkmcnt(4)
	v_mfma_f32_32x32x16_bf16 v[16:31], v[136:139], v[128:131], v[16:31]
	s_waitcnt lgkmcnt(3)
	v_mfma_f32_32x32x16_bf16 v[0:15], v[144:147], v[128:131], v[0:15]
	v_add_u32_e32 v156, 12, v36
	v_xor_b32_e32 v156, v156, v38
	v_lshl_add_u32 v157, v156, 4, v39
	ds_read_b128 v[128:131], v155 offset:192
	ds_read_b128 v[136:139], v157
	ds_read_b128 v[144:147], v157 offset:16384
	s_waitcnt lgkmcnt(4)
	v_mfma_f32_32x32x16_bf16 v[16:31], v[140:143], v[132:135], v[16:31]
	s_waitcnt lgkmcnt(3)
	v_mfma_f32_32x32x16_bf16 v[0:15], v[148:151], v[132:135], v[0:15]
	v_add_u32_e32 v156, 14, v36
	v_xor_b32_e32 v156, v156, v38
	v_lshl_add_u32 v157, v156, 4, v39
	ds_read_b128 v[132:135], v155 offset:224
	ds_read_b128 v[140:143], v157
	ds_read_b128 v[148:151], v157 offset:16384
	s_waitcnt lgkmcnt(4)
	v_mfma_f32_32x32x16_bf16 v[16:31], v[136:139], v[128:131], v[16:31]
	s_waitcnt lgkmcnt(3)
	v_mfma_f32_32x32x16_bf16 v[0:15], v[144:147], v[128:131], v[0:15]
	s_waitcnt lgkmcnt(1)
	v_mfma_f32_32x32x16_bf16 v[16:31], v[140:143], v[132:135], v[16:31]
	s_waitcnt lgkmcnt(0)
	v_mfma_f32_32x32x16_bf16 v[0:15], v[148:151], v[132:135], v[0:15]
	s_waitcnt vmcnt(0)
	ds_write_b128 v154, v[96:99] offset:0
	ds_write_b128 v154, v[100:103] offset:1088
	ds_write_b128 v154, v[104:107] offset:2176
	ds_write_b128 v154, v[108:111] offset:3264
	ds_write_b128 v154, v[112:115] offset:4352
	ds_write_b128 v154, v[116:119] offset:5440
	ds_write_b128 v154, v[120:123] offset:6528
	ds_write_b128 v154, v[124:127] offset:7616
	v_add_u32_e32 v156, 16, v36
	v_xor_b32_e32 v156, v156, v38
	v_lshl_add_u32 v157, v156, 4, v39
	ds_read_b128 v[128:131], v155 offset:0
	ds_read_b128 v[136:139], v157
	ds_read_b128 v[144:147], v157 offset:16384
	v_add_u32_e32 v156, 18, v36
	v_xor_b32_e32 v156, v156, v38
	v_lshl_add_u32 v157, v156, 4, v39
	ds_read_b128 v[132:135], v155 offset:32
	ds_read_b128 v[140:143], v157
	ds_read_b128 v[148:151], v157 offset:16384
	s_waitcnt lgkmcnt(4)
	v_mfma_f32_32x32x16_bf16 v[16:31], v[136:139], v[128:131], v[16:31]
	s_waitcnt lgkmcnt(3)
	v_mfma_f32_32x32x16_bf16 v[0:15], v[144:147], v[128:131], v[0:15]
	v_add_u32_e32 v156, 20, v36
	v_xor_b32_e32 v156, v156, v38
	v_lshl_add_u32 v157, v156, 4, v39
	ds_read_b128 v[128:131], v155 offset:64
	ds_read_b128 v[136:139], v157
	ds_read_b128 v[144:147], v157 offset:16384
	s_waitcnt lgkmcnt(4)
; #define LAS __attribute__((address_space(3)))
; __device__ __forceinline__ unsigned pk2(float lo, float hi) { return cvt_pk_bf16(lo, hi); }
; #define MFMA32(a, b, c) __builtin_amdgcn_mfma_f32_32x32x16_bf16(a, b, c, 0, 0, 0)
; __device__ __forceinline__ void cmp2_tile(const Params& P, const Ctx& C, int kv, int pm) {
;     ...
; #pragma unroll 8
;     for (int ks = 0; ks < 16; ++ks) { const bf16x8 hf = *(const bf16x8*)(HID + 16 * ks); const int so = (((2 * ks + hi) ^ (r32 & 15)) * 16);
;         a0 = MFMA32(*(const LAS bf16x8*)(wr0 + so), hf, a0); a1 = MFMA32(*(const LAS bf16x8*)(wr1 + so), hf, a1); }
;     bf16_t* O = (bf16_t*)(ws + (kv ? WS_VCC : WS_KCC)) + (size_t)(row0 + r32) * 64;
; #pragma unroll
;     for (int rq = 0; rq < 4; ++rq) { u32x2 w;
;         w.x = pk2(a0[4 * rq], a0[4 * rq + 1]); w.y = pk2(a0[4 * rq + 2], a0[4 * rq + 3]); *(u32x2*)(O + 8 * rq + 4 * hi) = w;
;         w.x = pk2(a1[4 * rq], a1[4 * rq + 1]); w.y = pk2(a1[4 * rq + 2], a1[4 * rq + 3]); *(u32x2*)(O + 32 + 8 * rq + 4 * hi) = w; }
	v_mfma_f32_32x32x16_bf16 v[16:31], v[140:143], v[132:135], v[16:31]
	s_waitcnt lgkmcnt(3)
	v_mfma_f32_32x32x16_bf16 v[0:15], v[148:151], v[132:135], v[0:15]
	v_add_u32_e32 v156, 22, v36
	v_xor_b32_e32 v156, v156, v38
	v_lshl_add_u32 v157, v156, 4, v39
	ds_read_b128 v[132:135], v155 offset:96
	ds_read_b128 v[140:143], v157
	ds_read_b128 v[148:151], v157 offset:16384
	s_waitcnt lgkmcnt(4)
	v_mfma_f32_32x32x16_bf16 v[16:31], v[136:139], v[128:131], v[16:31]
	s_waitcnt lgkmcnt(3)
	v_mfma_f32_32x32x16_bf16 v[0:15], v[144:147], v[128:131], v[0:15]
	v_add_u32_e32 v156, 24, v36
	v_xor_b32_e32 v156, v156, v38
	v_lshl_add_u32 v157, v156, 4, v39
	ds_read_b128 v[128:131], v155 offset:128
	ds_read_b128 v[136:139], v157
	ds_read_b128 v[144:147], v157 offset:16384
	s_waitcnt lgkmcnt(4)
	v_mfma_f32_32x32x16_bf16 v[16:31], v[140:143], v[132:135], v[16:31]
	s_waitcnt lgkmcnt(3)
	v_mfma_f32_32x32x16_bf16 v[0:15], v[148:151], v[132:135], v[0:15]
	v_add_u32_e32 v156, 26, v36
	v_xor_b32_e32 v156, v156, v38
	v_lshl_add_u32 v157, v156, 4, v39
	ds_read_b128 v[132:135], v155 offset:160
	ds_read_b128 v[140:143], v157
	ds_read_b128 v[148:151], v157 offset:16384
	s_waitcnt lgkmcnt(4)
	v_mfma_f32_32x32x16_bf16 v[16:31], v[136:139], v[128:131], v[16:31]
	s_waitcnt lgkmcnt(3)
	v_mfma_f32_32x32x16_bf16 v[0:15], v[144:147], v[128:131], v[0:15]
	v_add_u32_e32 v156, 28, v36
	v_xor_b32_e32 v156, v156, v38
	v_lshl_add_u32 v157, v156, 4, v39
	ds_read_b128 v[128:131], v155 offset:192
	ds_read_b128 v[136:139], v157
	ds_read_b128 v[144:147], v157 offset:16384
	s_waitcnt lgkmcnt(4)
	v_mfma_f32_32x32x16_bf16 v[16:31], v[140:143], v[132:135], v[16:31]
	s_waitcnt lgkmcnt(3)
	v_mfma_f32_32x32x16_bf16 v[0:15], v[148:151], v[132:135], v[0:15]
	v_add_u32_e32 v156, 30, v36
	v_xor_b32_e32 v156, v156, v38
	v_lshl_add_u32 v157, v156, 4, v39
	ds_read_b128 v[132:135], v155 offset:224
	ds_read_b128 v[140:143], v157
	ds_read_b128 v[148:151], v157 offset:16384
	s_waitcnt lgkmcnt(4)
	v_mfma_f32_32x32x16_bf16 v[16:31], v[136:139], v[128:131], v[16:31]
	s_waitcnt lgkmcnt(3)
	v_mfma_f32_32x32x16_bf16 v[0:15], v[144:147], v[128:131], v[0:15]
	s_waitcnt lgkmcnt(1)
	v_mfma_f32_32x32x16_bf16 v[16:31], v[140:143], v[132:135], v[16:31]
	s_waitcnt lgkmcnt(0)
	v_mfma_f32_32x32x16_bf16 v[0:15], v[148:151], v[132:135], v[0:15]
	s_nop 0
	s_and_b64 s[16:17], s[16:17], exec
	s_cselect_b32 s6, s20, 0x37700000
	v_or_b32_e32 v32, s23, v37
	s_add_u32 s14, s14, s6
	s_addc_u32 s15, s15, 0
	v_lshlrev_b64 v[34:35], 7, v[32:33]
	v_lshlrev_b32_e32 v36, 2, v36
	v_lshl_add_u64 v[34:35], s[14:15], 0, v[34:35]
	v_ashrrev_i32_e32 v37, 31, v36
	v_lshl_add_u64 v[34:35], v[36:37], 1, v[34:35]
	v_cvt_pk_bf16_f32 v16, v16, v17
	v_cvt_pk_bf16_f32 v17, v18, v19
	global_store_dwordx2 v[34:35], v[16:17], off
	v_cvt_pk_bf16_f32 v0, v0, v1
	v_cvt_pk_bf16_f32 v1, v2, v3
	global_store_dwordx2 v[34:35], v[0:1], off offset:64
	v_cvt_pk_bf16_f32 v0, v20, v21
	v_cvt_pk_bf16_f32 v1, v22, v23
	s_add_i32 s21, s21, 1
	global_store_dwordx2 v[34:35], v[0:1], off offset:16
	v_cvt_pk_bf16_f32 v0, v4, v5
	v_cvt_pk_bf16_f32 v1, v6, v7
	s_mul_i32 s6, s21, s68
	global_store_dwordx2 v[34:35], v[0:1], off offset:80
	v_cvt_pk_bf16_f32 v0, v24, v25
	v_cvt_pk_bf16_f32 v1, v26, v27
	s_add_i32 s14, s6, s87
	global_store_dwordx2 v[34:35], v[0:1], off offset:32
	v_cvt_pk_bf16_f32 v0, v8, v9
	v_cvt_pk_bf16_f32 v1, v10, v11
	s_and_b32 s40, s14, 15
	s_ashr_i32 s6, s14, 4
	global_store_dwordx2 v[34:35], v[0:1], off offset:96
	v_cvt_pk_bf16_f32 v0, v28, v29
	v_cvt_pk_bf16_f32 v1, v30, v31
	s_cmp_gt_i32 s14, 31
	global_store_dwordx2 v[34:35], v[0:1], off offset:48
	v_cvt_pk_bf16_f32 v0, v12, v13
	v_cvt_pk_bf16_f32 v1, v14, v15
	global_store_dwordx2 v[34:35], v[0:1], off offset:112
	s_cbranch_scc0 .LBB0_1112
